# S5 prompt tile: first-half C-multiply issued inside the scan, pack/store delayed; other levers as v26
# speedup vs baseline: 1.0072x; 1.0072x over previous
.Ls5p_swap:
	v_permlane32_swap_b32_e32 v0, v112
	v_permlane32_swap_b32_e32 v1, v113
	v_permlane32_swap_b32_e32 v2, v114
	v_permlane32_swap_b32_e32 v3, v115
	v_permlane32_swap_b32_e32 v4, v116
	v_permlane32_swap_b32_e32 v5, v117
	v_permlane32_swap_b32_e32 v6, v118
	v_permlane32_swap_b32_e32 v7, v119
	v_permlane32_swap_b32_e32 v8, v120
	v_permlane32_swap_b32_e32 v9, v121
	v_permlane32_swap_b32_e32 v10, v122
	v_permlane32_swap_b32_e32 v11, v123
	v_permlane32_swap_b32_e32 v12, v124
	v_permlane32_swap_b32_e32 v13, v125
	v_permlane32_swap_b32_e32 v14, v126
	v_permlane32_swap_b32_e32 v15, v127
	v_permlane32_swap_b32_e32 v16, v160
	v_permlane32_swap_b32_e32 v17, v161
	v_permlane32_swap_b32_e32 v18, v162
	v_permlane32_swap_b32_e32 v19, v163
	v_permlane32_swap_b32_e32 v20, v164
	v_permlane32_swap_b32_e32 v21, v165
	v_permlane32_swap_b32_e32 v22, v166
	v_permlane32_swap_b32_e32 v23, v167
	v_permlane32_swap_b32_e32 v24, v168
	v_permlane32_swap_b32_e32 v25, v169
	v_permlane32_swap_b32_e32 v26, v170
	v_permlane32_swap_b32_e32 v27, v171
	v_permlane32_swap_b32_e32 v28, v172
	v_permlane32_swap_b32_e32 v29, v173
	v_permlane32_swap_b32_e32 v30, v174
	v_permlane32_swap_b32_e32 v31, v175
	v_fmac_f32_e32 v0, v80, v103
	v_fmac_f32_e32 v16, v80, v102
	v_fmac_f32_e32 v0, v89, v102
	v_fmac_f32_e32 v16, v81, v103
	v_fmac_f32_e32 v1, v80, v0
	v_fmac_f32_e32 v17, v80, v16
	v_cvt_pk_bf16_f32 v134, v0, v16
	v_fmac_f32_e32 v1, v89, v16
	v_fmac_f32_e32 v17, v81, v0
	v_fmac_f32_e32 v2, v80, v1
	v_fmac_f32_e32 v18, v80, v17
	v_cvt_pk_bf16_f32 v135, v1, v17
	v_fmac_f32_e32 v2, v89, v17
	v_fmac_f32_e32 v18, v81, v1
	ds_write_b32 v107, v134
	v_fmac_f32_e32 v3, v80, v2
	v_fmac_f32_e32 v19, v80, v18
	v_cvt_pk_bf16_f32 v136, v2, v18
	v_fmac_f32_e32 v3, v89, v18
	v_fmac_f32_e32 v19, v81, v2
	ds_write_b32 v107, v135 offset:528
	v_fmac_f32_e32 v112, v80, v3
	v_fmac_f32_e32 v160, v80, v19
	v_cvt_pk_bf16_f32 v137, v3, v19
	v_fmac_f32_e32 v112, v89, v19
	v_fmac_f32_e32 v160, v81, v3
	ds_write_b32 v107, v136 offset:1056
	v_fmac_f32_e32 v113, v80, v112
	v_fmac_f32_e32 v161, v80, v160
	v_cvt_pk_bf16_f32 v138, v112, v160
	v_fmac_f32_e32 v113, v89, v160
	v_fmac_f32_e32 v161, v81, v112
	ds_write_b32 v107, v137 offset:1584
	v_fmac_f32_e32 v114, v80, v113
	v_fmac_f32_e32 v162, v80, v161
	v_cvt_pk_bf16_f32 v139, v113, v161
	v_fmac_f32_e32 v114, v89, v161
	v_fmac_f32_e32 v162, v81, v113
	ds_write_b32 v107, v138 offset:2112
	v_fmac_f32_e32 v115, v80, v114
	v_fmac_f32_e32 v163, v80, v162
	v_cvt_pk_bf16_f32 v134, v114, v162
	v_fmac_f32_e32 v115, v89, v162
	v_fmac_f32_e32 v163, v81, v114
	ds_write_b32 v107, v139 offset:2640
	v_fmac_f32_e32 v4, v80, v115
	v_fmac_f32_e32 v20, v80, v163
	v_cvt_pk_bf16_f32 v135, v115, v163
	v_fmac_f32_e32 v4, v89, v163
	v_fmac_f32_e32 v20, v81, v115
	ds_write_b32 v107, v134 offset:3168
	v_fmac_f32_e32 v5, v80, v4
	v_fmac_f32_e32 v21, v80, v20
	v_cvt_pk_bf16_f32 v136, v4, v20
	v_fmac_f32_e32 v5, v89, v20
	v_fmac_f32_e32 v21, v81, v4
	ds_write_b32 v107, v135 offset:3696
	v_fmac_f32_e32 v6, v80, v5
	v_fmac_f32_e32 v22, v80, v21
	v_cvt_pk_bf16_f32 v137, v5, v21
	v_fmac_f32_e32 v6, v89, v21
	v_fmac_f32_e32 v22, v81, v5
	ds_write_b32 v107, v136 offset:4224
	v_fmac_f32_e32 v7, v80, v6
	v_fmac_f32_e32 v23, v80, v22
	v_cvt_pk_bf16_f32 v138, v6, v22
	v_fmac_f32_e32 v7, v89, v22
	v_fmac_f32_e32 v23, v81, v6
	ds_write_b32 v107, v137 offset:4752
	v_fmac_f32_e32 v116, v80, v7
	v_fmac_f32_e32 v164, v80, v23
	v_cvt_pk_bf16_f32 v139, v7, v23
	v_fmac_f32_e32 v116, v89, v23
	v_fmac_f32_e32 v164, v81, v7
	ds_write_b32 v107, v138 offset:5280
	v_fmac_f32_e32 v117, v80, v116
	v_fmac_f32_e32 v165, v80, v164
	v_cvt_pk_bf16_f32 v134, v116, v164
	v_fmac_f32_e32 v117, v89, v164
	v_fmac_f32_e32 v165, v81, v116
	ds_write_b32 v107, v139 offset:5808
	v_fmac_f32_e32 v118, v80, v117
	v_fmac_f32_e32 v166, v80, v165
	v_cvt_pk_bf16_f32 v135, v117, v165
	v_fmac_f32_e32 v118, v89, v165
	v_fmac_f32_e32 v166, v81, v117
	ds_write_b32 v107, v134 offset:6336
	v_fmac_f32_e32 v119, v80, v118
	v_fmac_f32_e32 v167, v80, v166
	v_cvt_pk_bf16_f32 v136, v118, v166
	v_fmac_f32_e32 v119, v89, v166
	v_fmac_f32_e32 v167, v81, v118
	ds_write_b32 v107, v135 offset:6864
	v_fmac_f32_e32 v8, v80, v119
	v_fmac_f32_e32 v24, v80, v167
	v_cvt_pk_bf16_f32 v137, v119, v167
	v_fmac_f32_e32 v8, v89, v167
	v_fmac_f32_e32 v24, v81, v119
	ds_write_b32 v107, v136 offset:7392
	v_fmac_f32_e32 v9, v80, v8
	v_fmac_f32_e32 v25, v80, v24
	v_cvt_pk_bf16_f32 v138, v8, v24
	v_fmac_f32_e32 v9, v89, v24
	v_fmac_f32_e32 v25, v81, v8
	ds_write_b32 v107, v137 offset:7920
	ds_read_b128 v[194:197], v108
	ds_read_b128 v[198:201], v108 offset:64
	ds_read_b128 v[202:205], v108 offset:128
	ds_read_b128 v[206:209], v108 offset:192
	v_fmac_f32_e32 v10, v80, v9
	v_fmac_f32_e32 v26, v80, v25
	v_cvt_pk_bf16_f32 v139, v9, v25
	v_fmac_f32_e32 v10, v89, v25
	v_fmac_f32_e32 v26, v81, v9
	ds_write_b32 v107, v138 offset:8448
	v_fmac_f32_e32 v11, v80, v10
	v_fmac_f32_e32 v27, v80, v26
	v_cvt_pk_bf16_f32 v134, v10, v26
	v_fmac_f32_e32 v11, v89, v26
	v_fmac_f32_e32 v27, v81, v10
	ds_write_b32 v107, v139 offset:8976
	v_fmac_f32_e32 v120, v80, v11
	v_fmac_f32_e32 v168, v80, v27
	v_cvt_pk_bf16_f32 v135, v11, v27
	v_fmac_f32_e32 v120, v89, v27
	v_fmac_f32_e32 v168, v81, v11
	ds_write_b32 v107, v134 offset:9504
	v_fmac_f32_e32 v121, v80, v120
	v_fmac_f32_e32 v169, v80, v168
	v_cvt_pk_bf16_f32 v136, v120, v168
	v_fmac_f32_e32 v121, v89, v168
	v_fmac_f32_e32 v169, v81, v120
	ds_write_b32 v107, v135 offset:10032
	v_fmac_f32_e32 v122, v80, v121
	v_fmac_f32_e32 v170, v80, v169
	v_cvt_pk_bf16_f32 v137, v121, v169
	v_fmac_f32_e32 v122, v89, v169
	v_fmac_f32_e32 v170, v81, v121
	ds_write_b32 v107, v136 offset:10560
	s_waitcnt lgkmcnt(5)
	v_mfma_f32_16x16x32_bf16 v[226:229], v[48:51], v[194:197], 0
	v_fmac_f32_e32 v123, v80, v122
	v_fmac_f32_e32 v171, v80, v170
	v_cvt_pk_bf16_f32 v138, v122, v170
	v_fmac_f32_e32 v123, v89, v170
	v_fmac_f32_e32 v171, v81, v122
	ds_write_b32 v107, v137 offset:11088
	v_mfma_f32_16x16x32_bf16 v[226:229], v[52:55], v[198:201], v[226:229]
	v_fmac_f32_e32 v12, v80, v123
	v_fmac_f32_e32 v28, v80, v171
	v_cvt_pk_bf16_f32 v139, v123, v171
	v_fmac_f32_e32 v12, v89, v171
	v_fmac_f32_e32 v28, v81, v123
	ds_write_b32 v107, v138 offset:11616
	v_mfma_f32_16x16x32_bf16 v[226:229], v[56:59], v[202:205], v[226:229]
	v_fmac_f32_e32 v13, v80, v12
	v_fmac_f32_e32 v29, v80, v28
	v_cvt_pk_bf16_f32 v134, v12, v28
	v_fmac_f32_e32 v13, v89, v28
	v_fmac_f32_e32 v29, v81, v12
	ds_write_b32 v107, v139 offset:12144
	v_mfma_f32_16x16x32_bf16 v[226:229], v[60:63], v[206:209], v[226:229]
	v_fmac_f32_e32 v14, v80, v13
	v_fmac_f32_e32 v30, v80, v29
	v_cvt_pk_bf16_f32 v135, v13, v29
	v_fmac_f32_e32 v14, v89, v29
	v_fmac_f32_e32 v30, v81, v13
	ds_write_b32 v107, v134 offset:12672
	v_fmac_f32_e32 v15, v80, v14
	v_fmac_f32_e32 v31, v80, v30
	v_cvt_pk_bf16_f32 v136, v14, v30
	v_fmac_f32_e32 v15, v89, v30
	v_fmac_f32_e32 v31, v81, v14
	ds_write_b32 v107, v135 offset:13200
	v_fmac_f32_e32 v124, v80, v15
	v_fmac_f32_e32 v172, v80, v31
	v_cvt_pk_bf16_f32 v137, v15, v31
	v_fmac_f32_e32 v124, v89, v31
	v_fmac_f32_e32 v172, v81, v15
	ds_write_b32 v107, v136 offset:13728
	v_fmac_f32_e32 v125, v80, v124
	v_fmac_f32_e32 v173, v80, v172
	v_cvt_pk_bf16_f32 v138, v124, v172
	v_fmac_f32_e32 v125, v89, v172
	v_fmac_f32_e32 v173, v81, v124
	ds_write_b32 v107, v137 offset:14256
	v_fmac_f32_e32 v126, v80, v125
	v_fmac_f32_e32 v174, v80, v173
	v_cvt_pk_bf16_f32 v139, v125, v173
	v_fmac_f32_e32 v126, v89, v173
	v_fmac_f32_e32 v174, v81, v125
	ds_write_b32 v107, v138 offset:14784
	v_fma_f32 v103, v80, v126, v127
	v_fma_f32 v102, v80, v174, v175
	v_cvt_pk_bf16_f32 v134, v126, v174
	v_fmac_f32_e32 v103, v89, v174
	v_fmac_f32_e32 v102, v81, v126
	ds_write_b32 v107, v139 offset:15312
	v_cvt_pk_bf16_f32 v135, v103, v102
	ds_write_b32 v107, v134 offset:15840
	ds_write_b32 v107, v135 offset:16368
	v_mov_b64_e32 v[18:19], s[16:17]
	v_add_u32_e32 v4, s5, v110
	ds_read_b128 v[194:197], v108 offset:8448
	ds_read_b128 v[198:201], v108 offset:8512
	ds_read_b128 v[202:205], v108 offset:8576
	ds_read_b128 v[206:209], v108 offset:8640
	v_ashrrev_i32_e32 v5, 31, v4
	v_lshlrev_b32_e32 v10, 16, v100
	v_and_b32_e32 v11, 0xffff0000, v100
	v_pk_fma_f32 v[14:15], v[64:65], v[10:11], v[226:227]
	s_nop 0
	v_pk_mul_f32 v[6:7], v[14:15], v[14:15]
	s_nop 0
	v_pk_fma_f32 v[6:7], v[6:7], s[10:11], v[18:19] op_sel_hi:[1,0,0] neg_lo:[1,0,0] neg_hi:[1,0,0]
	s_nop 0
	v_pk_mul_f32 v[6:7], v[14:15], v[6:7]
	s_nop 0
	v_exp_f32_e32 v6, v6
	v_exp_f32_e32 v7, v7
	s_nop 0
	v_pk_add_f32 v[10:11], v[6:7], 1.0 op_sel_hi:[1,0]
	v_lshlrev_b32_e32 v6, 16, v101
	v_and_b32_e32 v7, 0xffff0000, v101
	v_pk_fma_f32 v[20:21], v[66:67], v[6:7], v[228:229]
	v_rcp_f32_e32 v16, v10
	v_pk_mul_f32 v[6:7], v[20:21], v[20:21]
	v_rcp_f32_e32 v17, v11
	v_pk_fma_f32 v[6:7], v[6:7], s[10:11], v[18:19] op_sel_hi:[1,0,0] neg_lo:[1,0,0] neg_hi:[1,0,0]
	s_nop 0
	s_nop 0
	v_pk_mul_f32 v[6:7], v[20:21], v[6:7]
	v_pk_mul_f32 v[24:25], v[14:15], v[16:17]
	v_exp_f32_e32 v12, v6
	v_exp_f32_e32 v13, v7
	s_nop 0
	v_pk_add_f32 v[22:23], v[12:13], 1.0 op_sel_hi:[1,0]
	s_waitcnt lgkmcnt(3)
	v_mfma_f32_16x16x32_bf16 v[6:9], v[48:51], v[194:197], 0
	v_rcp_f32_e32 v22, v22
	v_rcp_f32_e32 v23, v23
	s_waitcnt lgkmcnt(2)
	v_mfma_f32_16x16x32_bf16 v[6:9], v[52:55], v[198:201], v[6:9]
	v_pk_mul_f32 v[20:21], v[20:21], v[22:23]
	v_cvt_pk_bf16_f32 v22, v24, v25
	s_waitcnt lgkmcnt(1)
	v_mfma_f32_16x16x32_bf16 v[6:9], v[56:59], v[202:205], v[6:9]
	v_lshlrev_b64 v[14:15], 12, v[4:5]
	v_add_u32_e32 v4, 16, v4
	v_ashrrev_i32_e32 v5, 31, v4
	s_waitcnt lgkmcnt(0)
	v_mfma_f32_16x16x32_bf16 v[6:9], v[60:63], v[206:209], v[6:9]
	v_lshlrev_b32_e32 v10, 16, v94
	v_and_b32_e32 v11, 0xffff0000, v94
	v_lshlrev_b32_e32 v12, 16, v95
	v_and_b32_e32 v13, 0xffff0000, v95
	v_lshlrev_b64 v[4:5], 12, v[4:5]
	s_nop 2
	v_pk_fma_f32 v[6:7], v[64:65], v[10:11], v[6:7]
	v_pk_fma_f32 v[8:9], v[66:67], v[12:13], v[8:9]
	v_pk_mul_f32 v[10:11], v[6:7], v[6:7]
	v_pk_mul_f32 v[12:13], v[8:9], v[8:9]
	v_pk_fma_f32 v[10:11], v[10:11], s[10:11], v[18:19] op_sel_hi:[1,0,0] neg_lo:[1,0,0] neg_hi:[1,0,0]
	v_pk_fma_f32 v[12:13], v[12:13], s[10:11], v[18:19] op_sel_hi:[1,0,0] neg_lo:[1,0,0] neg_hi:[1,0,0]
	v_pk_mul_f32 v[10:11], v[6:7], v[10:11]
	v_pk_mul_f32 v[12:13], v[8:9], v[12:13]
	v_exp_f32_e32 v10, v10
	v_exp_f32_e32 v11, v11
	v_exp_f32_e32 v12, v12
	v_exp_f32_e32 v13, v13
	v_lshl_add_u64 v[14:15], v[82:83], 0, v[14:15]
	v_pk_add_f32 v[10:11], v[10:11], 1.0 op_sel_hi:[1,0]
	v_lshl_add_u64 v[4:5], v[82:83], 0, v[4:5]
	v_rcp_f32_e32 v10, v10
	v_rcp_f32_e32 v11, v11
	v_pk_add_f32 v[12:13], v[12:13], 1.0 op_sel_hi:[1,0]
	v_cvt_pk_bf16_f32 v23, v20, v21
	global_store_dwordx2 v[14:15], v[22:23], off
	v_rcp_f32_e32 v12, v12
	v_rcp_f32_e32 v13, v13
	v_pk_mul_f32 v[6:7], v[6:7], v[10:11]
	s_nop 0
	s_nop 0
	v_cvt_pk_bf16_f32 v6, v6, v7
	v_pk_mul_f32 v[8:9], v[8:9], v[12:13]
	s_nop 0
	v_cvt_pk_bf16_f32 v7, v8, v9
	global_store_dwordx2 v[4:5], v[6:7], off
	s_add_i32 s5, s5, 32
	s_add_i32 s6, s6, 1
	s_waitcnt vmcnt(2)
	v_mov_b64_e32 v[100:101], v[190:191]
	v_mov_b64_e32 v[94:95], v[192:193]
	s_cmp_lt_u32 s6, 64
	s_cbranch_scc1 .Ls5p_tile
	s_branch .LBB0_463
